# LN2 in-loop: batched wave reductions + vmcnt no longer waits on previous stores
# speedup vs baseline: 1.0009x; 1.0009x over previous
; __device__ __forceinline__ size_t ytile(int row, int col) { return ((((size_t)(row >> 8) * 16) + (col >> 8)) * 256 + (row & 255)) * 256 + (col & 255); }
; template <bool LN1>
; __device__ __forceinline__ void ln_phase(Frame& F, const bf16_t* Yin, const float* ga, const float* be, const float* modf, float* stats, bf16_t* ob16, float* of32) {
;     ...
;     for (int rb = F.vcu * 64; rb < T; rb += F.G * 64) {
;         const int b = rb / S;
;         f32x4 ca[2], cb[2];
; #pragma unroll
;         for (int n = 0; n < 2; ++n) {
;             if (LN1) { const f32x4 sc1 = *(const f32x4*)(modf + (size_t)b * NADA + 4 * D + c0 + 4 * n) + 1.0f, sh = *(const f32x4*)(modf + (size_t)b * NADA + 3 * D + c0 + 4 * n);
;                 ca[n] = *(const f32x4*)(ga + c0 + 4 * n) * sc1; cb[n] = *(const f32x4*)(be + c0 + 4 * n) * sc1 + sh; }
;             else { ca[n] = *(const f32x4*)(ga + c0 + 4 * n); cb[n] = *(const f32x4*)(be + c0 + 4 * n); }
;         }
;         u32x4 nx[8];
; #pragma unroll
;         for (int k = 0; k < 8; ++k) nx[k] = *(const u32x4*)(Yin + ytile(rb + k, c0));
.LBB0_1343:
	s_ashr_i32 s2, s4, 8
	s_ashr_i32 s3, s2, 31
	s_lshl_b64 s[2:3], s[2:3], 12
	v_lshl_add_u64 v[16:17], s[2:3], 0, v[48:49]
	s_and_b32 s2, s4, 0xc0
	v_or_b32_e32 v18, s2, v16
	v_mov_b32_e32 v19, v17
	v_lshlrev_b64 v[18:19], 9, v[18:19]
	v_or3_b32 v20, s2, 1, v16
	v_mov_b32_e32 v21, v17
	v_lshl_add_u64 v[18:19], v[54:55], 0, v[18:19]
	v_lshlrev_b64 v[20:21], 9, v[20:21]
	global_load_dwordx4 v[0:3], v[50:51], off offset:16
	global_load_dwordx4 v[8:11], v[50:51], off
	s_waitcnt lgkmcnt(0)
	global_load_dwordx4 v[4:7], v[52:53], off offset:16
	global_load_dwordx4 v[12:15], v[52:53], off
	v_lshl_add_u64 v[20:21], v[54:55], 0, v[20:21]
	global_load_dwordx4 v[44:47], v[18:19], off
	global_load_dwordx4 v[40:43], v[20:21], off
	v_or3_b32 v18, s2, 2, v16
	v_mov_b32_e32 v19, v17
	v_lshlrev_b64 v[18:19], 9, v[18:19]
	v_or3_b32 v20, s2, 3, v16
	v_mov_b32_e32 v21, v17
	v_lshl_add_u64 v[18:19], v[54:55], 0, v[18:19]
	v_lshlrev_b64 v[20:21], 9, v[20:21]
	v_lshl_add_u64 v[20:21], v[54:55], 0, v[20:21]
	global_load_dwordx4 v[36:39], v[18:19], off
	global_load_dwordx4 v[32:35], v[20:21], off
	v_or3_b32 v18, s2, 4, v16
	v_mov_b32_e32 v19, v17
	v_lshlrev_b64 v[18:19], 9, v[18:19]
	v_or3_b32 v20, s2, 5, v16
	v_mov_b32_e32 v21, v17
	v_lshl_add_u64 v[18:19], v[54:55], 0, v[18:19]
	v_lshlrev_b64 v[20:21], 9, v[20:21]
	v_lshl_add_u64 v[20:21], v[54:55], 0, v[20:21]
	global_load_dwordx4 v[28:31], v[18:19], off
	global_load_dwordx4 v[24:27], v[20:21], off
	v_or3_b32 v18, s2, 6, v16
	v_mov_b32_e32 v19, v17
	v_lshlrev_b64 v[18:19], 9, v[18:19]
	v_or3_b32 v16, s2, 7, v16
	v_lshl_add_u64 v[60:61], v[54:55], 0, v[18:19]
	v_lshlrev_b64 v[16:17], 9, v[16:17]
	v_lshl_add_u64 v[62:63], v[54:55], 0, v[16:17]
	global_load_dwordx4 v[20:23], v[60:61], off
	global_load_dwordx4 v[16:19], v[62:63], off
	v_mov_b64_e32 v[60:61], v[58:59]
	s_mov_b32 s7, 0
	s_mov_b32 s15, 0
	s_waitcnt vmcnt(0)
	s_branch .LBB0_1345

; #define LAS __attribute__((address_space(3)))
; template <bool LN1>
; __device__ __forceinline__ void ln_phase(Frame& F, const bf16_t* Yin, const float* ga, const float* be, const float* modf, float* stats, bf16_t* ob16, float* of32) {
;     ...
;         for (int bt = 0; bt < 8; ++bt) {
;             const int r0 = rb + 8 * bt; f32x4 v[8][2];
;             LAS f32x2* rd = red + (bt & 1) * 64;
; #pragma unroll
;             for (int k = 0; k < 8; ++k) { pg8::unpack8(nx[k], v[k][0], v[k][1]);
;                 float s = ((v[k][0][0] + v[k][0][1]) + (v[k][0][2] + v[k][0][3])) + ((v[k][1][0] + v[k][1][1]) + (v[k][1][2] + v[k][1][3]));
;                 float q = ((v[k][0][0] * v[k][0][0] + v[k][0][1] * v[k][0][1]) + (v[k][0][2] * v[k][0][2] + v[k][0][3] * v[k][0][3])) + ((v[k][1][0] * v[k][1][0] + v[k][1][1] * v[k][1][1]) + (v[k][1][2] * v[k][1][2] + v[k][1][3] * v[k][1][3]));
;                 s = wave_sum(s); q = wave_sum(q);
;                 if (lane == 0) rd[k * 8 + w] = (f32x2){s, q}; }
.LBB0_1345:
	s_waitcnt vmcnt(23)
	v_lshlrev_b32_e32 v182, 16, v44
	v_and_b32_e32 v184, 0xffff0000, v44
	v_lshlrev_b32_e32 v186, 16, v45
	v_and_b32_e32 v188, 0xffff0000, v45
	v_lshlrev_b32_e32 v148, 16, v46
	v_and_b32_e32 v168, 0xffff0000, v46
	v_lshlrev_b32_e32 v178, 16, v47
	v_and_b32_e32 v180, 0xffff0000, v47
	v_mul_f32_e32 v183, v182, v182
	v_mul_f32_e32 v185, v184, v184
	v_mul_f32_e32 v187, v186, v186
	v_mul_f32_e32 v189, v188, v188
	v_mul_f32_e32 v149, v148, v148
	v_mul_f32_e32 v169, v168, v168
	v_mul_f32_e32 v179, v178, v178
	v_mul_f32_e32 v181, v180, v180
	v_pk_add_f32 v[216:217], v[182:183], v[184:185]
	v_pk_add_f32 v[218:219], v[186:187], v[188:189]
	v_pk_add_f32 v[252:253], v[178:179], v[180:181]
	v_pk_add_f32 v[216:217], v[216:217], v[218:219]
	v_pk_add_f32 v[218:219], v[148:149], v[168:169]
	s_and_b32 s2, s7, 64
	v_pk_add_f32 v[218:219], v[218:219], v[252:253]
	s_lshl_b32 s2, s2, 3
	v_pk_add_f32 v[216:217], v[216:217], v[218:219]
	s_add_i32 s17, s2, 0
	s_add_i32 s16, s17, s11
	s_waitcnt vmcnt(22)
	v_lshlrev_b32_e32 v170, 16, v40
	v_and_b32_e32 v172, 0xffff0000, v40
	v_lshlrev_b32_e32 v174, 16, v41
	v_and_b32_e32 v176, 0xffff0000, v41
	v_lshlrev_b32_e32 v134, 16, v42
	v_and_b32_e32 v154, 0xffff0000, v42
	v_lshlrev_b32_e32 v164, 16, v43
	v_and_b32_e32 v166, 0xffff0000, v43
	v_mul_f32_e32 v171, v170, v170
	v_mul_f32_e32 v173, v172, v172
	v_mul_f32_e32 v175, v174, v174
	v_mul_f32_e32 v177, v176, v176
	v_mul_f32_e32 v135, v134, v134
	v_mul_f32_e32 v155, v154, v154
	v_mul_f32_e32 v165, v164, v164
	v_mul_f32_e32 v167, v166, v166
	v_pk_add_f32 v[220:221], v[170:171], v[172:173]
	v_pk_add_f32 v[222:223], v[174:175], v[176:177]
	v_pk_add_f32 v[252:253], v[164:165], v[166:167]
	v_pk_add_f32 v[220:221], v[220:221], v[222:223]
	v_pk_add_f32 v[222:223], v[134:135], v[154:155]
	s_nop 0
	v_pk_add_f32 v[222:223], v[222:223], v[252:253]
	s_nop 0
	v_pk_add_f32 v[220:221], v[220:221], v[222:223]
	s_waitcnt vmcnt(21)
	v_lshlrev_b32_e32 v156, 16, v36
	v_and_b32_e32 v158, 0xffff0000, v36
	v_lshlrev_b32_e32 v160, 16, v37
	v_and_b32_e32 v162, 0xffff0000, v37
	v_lshlrev_b32_e32 v118, 16, v38
	v_and_b32_e32 v138, 0xffff0000, v38
	v_lshlrev_b32_e32 v150, 16, v39
	v_and_b32_e32 v152, 0xffff0000, v39
	v_mul_f32_e32 v157, v156, v156
	v_mul_f32_e32 v159, v158, v158
	v_mul_f32_e32 v161, v160, v160
	v_mul_f32_e32 v163, v162, v162
	v_mul_f32_e32 v119, v118, v118
	v_mul_f32_e32 v139, v138, v138
	v_mul_f32_e32 v151, v150, v150
	v_mul_f32_e32 v153, v152, v152
	v_pk_add_f32 v[224:225], v[156:157], v[158:159]
	v_pk_add_f32 v[226:227], v[160:161], v[162:163]
	v_pk_add_f32 v[252:253], v[150:151], v[152:153]
	v_pk_add_f32 v[224:225], v[224:225], v[226:227]
	v_pk_add_f32 v[226:227], v[118:119], v[138:139]
	s_nop 0
	v_pk_add_f32 v[226:227], v[226:227], v[252:253]
	s_nop 0
	v_pk_add_f32 v[224:225], v[224:225], v[226:227]
	s_waitcnt vmcnt(20)
	v_lshlrev_b32_e32 v140, 16, v32
	v_and_b32_e32 v142, 0xffff0000, v32
	v_lshlrev_b32_e32 v144, 16, v33
	v_and_b32_e32 v146, 0xffff0000, v33
	v_lshlrev_b32_e32 v102, 16, v34
	v_and_b32_e32 v122, 0xffff0000, v34
	v_lshlrev_b32_e32 v132, 16, v35
	v_and_b32_e32 v136, 0xffff0000, v35
	v_mul_f32_e32 v141, v140, v140
	v_mul_f32_e32 v143, v142, v142
	v_mul_f32_e32 v145, v144, v144
	v_mul_f32_e32 v147, v146, v146
	v_mul_f32_e32 v103, v102, v102
	v_mul_f32_e32 v123, v122, v122
	v_mul_f32_e32 v133, v132, v132
	v_mul_f32_e32 v137, v136, v136
	v_pk_add_f32 v[228:229], v[140:141], v[142:143]
	v_pk_add_f32 v[230:231], v[144:145], v[146:147]
	v_pk_add_f32 v[252:253], v[132:133], v[136:137]
	v_pk_add_f32 v[228:229], v[228:229], v[230:231]
	v_pk_add_f32 v[230:231], v[102:103], v[122:123]
	s_nop 0
	v_pk_add_f32 v[230:231], v[230:231], v[252:253]
	s_nop 0
	v_pk_add_f32 v[228:229], v[228:229], v[230:231]
	s_waitcnt vmcnt(19)
	v_lshlrev_b32_e32 v124, 16, v28
	v_and_b32_e32 v126, 0xffff0000, v28
	v_lshlrev_b32_e32 v128, 16, v29
	v_and_b32_e32 v130, 0xffff0000, v29
	v_lshlrev_b32_e32 v86, 16, v30
	v_and_b32_e32 v106, 0xffff0000, v30
	v_lshlrev_b32_e32 v116, 16, v31
	v_and_b32_e32 v120, 0xffff0000, v31
	v_mul_f32_e32 v125, v124, v124
	v_mul_f32_e32 v127, v126, v126
	v_mul_f32_e32 v129, v128, v128
	v_mul_f32_e32 v131, v130, v130
	v_mul_f32_e32 v87, v86, v86
	v_mul_f32_e32 v107, v106, v106
	v_mul_f32_e32 v117, v116, v116
	v_mul_f32_e32 v121, v120, v120
	v_pk_add_f32 v[232:233], v[124:125], v[126:127]
	v_pk_add_f32 v[234:235], v[128:129], v[130:131]
	v_pk_add_f32 v[252:253], v[116:117], v[120:121]
	v_pk_add_f32 v[232:233], v[232:233], v[234:235]
	v_pk_add_f32 v[234:235], v[86:87], v[106:107]
	s_nop 0
	v_pk_add_f32 v[234:235], v[234:235], v[252:253]
	s_nop 0
	v_pk_add_f32 v[232:233], v[232:233], v[234:235]
	s_waitcnt vmcnt(18)
	v_lshlrev_b32_e32 v108, 16, v24
	v_and_b32_e32 v110, 0xffff0000, v24
	v_lshlrev_b32_e32 v112, 16, v25
	v_and_b32_e32 v114, 0xffff0000, v25
	v_lshlrev_b32_e32 v70, 16, v26
	v_and_b32_e32 v90, 0xffff0000, v26
	v_lshlrev_b32_e32 v100, 16, v27
	v_and_b32_e32 v104, 0xffff0000, v27
	v_mul_f32_e32 v109, v108, v108
	v_mul_f32_e32 v111, v110, v110
	v_mul_f32_e32 v113, v112, v112
	v_mul_f32_e32 v115, v114, v114
	v_mul_f32_e32 v71, v70, v70
	v_mul_f32_e32 v91, v90, v90
	v_mul_f32_e32 v101, v100, v100
	v_mul_f32_e32 v105, v104, v104
	v_pk_add_f32 v[236:237], v[108:109], v[110:111]
	v_pk_add_f32 v[238:239], v[112:113], v[114:115]
	v_pk_add_f32 v[252:253], v[100:101], v[104:105]
	v_pk_add_f32 v[236:237], v[236:237], v[238:239]
	v_pk_add_f32 v[238:239], v[70:71], v[90:91]
	s_nop 0
	v_pk_add_f32 v[238:239], v[238:239], v[252:253]
	s_nop 0
	v_pk_add_f32 v[236:237], v[236:237], v[238:239]
	s_waitcnt vmcnt(17)
; __device__ __forceinline__ float wave_sum(float v) {
; #pragma unroll
;     for (int o = 1; o < 64; o <<= 1) v += __shfl_xor(v, o);
;     return v;
; template <bool LN1>
; __device__ __forceinline__ void ln_phase(Frame& F, const bf16_t* Yin, const float* ga, const float* be, const float* modf, float* stats, bf16_t* ob16, float* of32) {
;     ...
;             for (int k = 0; k < 8; ++k) { pg8::unpack8(nx[k], v[k][0], v[k][1]);
;                 float s = ((v[k][0][0] + v[k][0][1]) + (v[k][0][2] + v[k][0][3])) + ((v[k][1][0] + v[k][1][1]) + (v[k][1][2] + v[k][1][3]));
;                 float q = ((v[k][0][0] * v[k][0][0] + v[k][0][1] * v[k][0][1]) + (v[k][0][2] * v[k][0][2] + v[k][0][3] * v[k][0][3])) + ((v[k][1][0] * v[k][1][0] + v[k][1][1] * v[k][1][1]) + (v[k][1][2] * v[k][1][2] + v[k][1][3] * v[k][1][3]));
;                 s = wave_sum(s); q = wave_sum(q);
;                 if (lane == 0) rd[k * 8 + w] = (f32x2){s, q}; }
	v_lshlrev_b32_e32 v92, 16, v20
	v_and_b32_e32 v94, 0xffff0000, v20
	v_lshlrev_b32_e32 v96, 16, v21
	v_and_b32_e32 v98, 0xffff0000, v21
	v_lshlrev_b32_e32 v62, 16, v22
	v_and_b32_e32 v74, 0xffff0000, v22
	v_lshlrev_b32_e32 v84, 16, v23
	v_and_b32_e32 v88, 0xffff0000, v23
	v_mul_f32_e32 v93, v92, v92
	v_mul_f32_e32 v95, v94, v94
	v_mul_f32_e32 v97, v96, v96
	v_mul_f32_e32 v99, v98, v98
	v_mul_f32_e32 v63, v62, v62
	v_mul_f32_e32 v75, v74, v74
	v_mul_f32_e32 v85, v84, v84
	v_mul_f32_e32 v89, v88, v88
	v_pk_add_f32 v[240:241], v[92:93], v[94:95]
	v_pk_add_f32 v[242:243], v[96:97], v[98:99]
	v_pk_add_f32 v[252:253], v[84:85], v[88:89]
	v_pk_add_f32 v[240:241], v[240:241], v[242:243]
	v_pk_add_f32 v[242:243], v[62:63], v[74:75]
	s_nop 0
	v_pk_add_f32 v[242:243], v[242:243], v[252:253]
	s_nop 0
	v_pk_add_f32 v[240:241], v[240:241], v[242:243]
	s_waitcnt vmcnt(16)
	v_lshlrev_b32_e32 v76, 16, v16
	v_and_b32_e32 v78, 0xffff0000, v16
	v_lshlrev_b32_e32 v80, 16, v17
	v_and_b32_e32 v82, 0xffff0000, v17
	v_lshlrev_b32_e32 v64, 16, v18
	v_and_b32_e32 v66, 0xffff0000, v18
	v_lshlrev_b32_e32 v68, 16, v19
	v_and_b32_e32 v72, 0xffff0000, v19
	v_mul_f32_e32 v77, v76, v76
	v_mul_f32_e32 v79, v78, v78
	v_mul_f32_e32 v81, v80, v80
	v_mul_f32_e32 v83, v82, v82
	v_mul_f32_e32 v65, v64, v64
	v_mul_f32_e32 v67, v66, v66
	v_mul_f32_e32 v69, v68, v68
	v_mul_f32_e32 v73, v72, v72
	v_pk_add_f32 v[248:249], v[76:77], v[78:79]
	v_pk_add_f32 v[250:251], v[80:81], v[82:83]
	v_pk_add_f32 v[252:253], v[68:69], v[72:73]
	v_pk_add_f32 v[248:249], v[248:249], v[250:251]
	v_pk_add_f32 v[250:251], v[64:65], v[66:67]
	s_nop 0
	v_pk_add_f32 v[250:251], v[250:251], v[252:253]
	s_nop 0
	v_pk_add_f32 v[248:249], v[248:249], v[250:251]
	ds_bpermute_b32 v218, v190, v216
	ds_bpermute_b32 v219, v190, v217
	ds_bpermute_b32 v222, v190, v220
	ds_bpermute_b32 v223, v190, v221
	ds_bpermute_b32 v226, v190, v224
	ds_bpermute_b32 v227, v190, v225
	ds_bpermute_b32 v230, v190, v228
	ds_bpermute_b32 v231, v190, v229
	ds_bpermute_b32 v234, v190, v232
	ds_bpermute_b32 v235, v190, v233
	ds_bpermute_b32 v238, v190, v236
	ds_bpermute_b32 v239, v190, v237
	s_waitcnt lgkmcnt(6)
	v_pk_add_f32 v[216:217], v[216:217], v[218:219]
	v_pk_add_f32 v[220:221], v[220:221], v[222:223]
	v_pk_add_f32 v[224:225], v[224:225], v[226:227]
	ds_bpermute_b32 v242, v190, v240
	ds_bpermute_b32 v243, v190, v241
	ds_bpermute_b32 v250, v190, v248
	ds_bpermute_b32 v251, v190, v249
	s_waitcnt lgkmcnt(4)
	v_pk_add_f32 v[228:229], v[228:229], v[230:231]
	v_pk_add_f32 v[232:233], v[232:233], v[234:235]
	v_pk_add_f32 v[236:237], v[236:237], v[238:239]
	ds_bpermute_b32 v218, v191, v216
	ds_bpermute_b32 v219, v191, v217
	ds_bpermute_b32 v222, v191, v220
	ds_bpermute_b32 v223, v191, v221
	ds_bpermute_b32 v226, v191, v224
	ds_bpermute_b32 v227, v191, v225
	s_waitcnt lgkmcnt(6)
	v_pk_add_f32 v[240:241], v[240:241], v[242:243]
	v_pk_add_f32 v[248:249], v[248:249], v[250:251]
	ds_bpermute_b32 v230, v191, v228
	ds_bpermute_b32 v231, v191, v229
	ds_bpermute_b32 v234, v191, v232
	ds_bpermute_b32 v235, v191, v233
	ds_bpermute_b32 v238, v191, v236
	ds_bpermute_b32 v239, v191, v237
	s_waitcnt lgkmcnt(6)
	v_pk_add_f32 v[216:217], v[216:217], v[218:219]
	v_pk_add_f32 v[220:221], v[220:221], v[222:223]
	v_pk_add_f32 v[224:225], v[224:225], v[226:227]
	ds_bpermute_b32 v242, v191, v240
	ds_bpermute_b32 v243, v191, v241
	ds_bpermute_b32 v250, v191, v248
	ds_bpermute_b32 v251, v191, v249
	s_waitcnt lgkmcnt(4)
	v_pk_add_f32 v[228:229], v[228:229], v[230:231]
	v_pk_add_f32 v[232:233], v[232:233], v[234:235]
	v_pk_add_f32 v[236:237], v[236:237], v[238:239]
	ds_bpermute_b32 v218, v192, v216
	ds_bpermute_b32 v219, v192, v217
	ds_bpermute_b32 v222, v192, v220
	ds_bpermute_b32 v223, v192, v221
	ds_bpermute_b32 v226, v192, v224
	ds_bpermute_b32 v227, v192, v225
	s_waitcnt lgkmcnt(6)
	v_pk_add_f32 v[240:241], v[240:241], v[242:243]
	v_pk_add_f32 v[248:249], v[248:249], v[250:251]
	ds_bpermute_b32 v230, v192, v228
	ds_bpermute_b32 v231, v192, v229
	ds_bpermute_b32 v234, v192, v232
	ds_bpermute_b32 v235, v192, v233
	ds_bpermute_b32 v238, v192, v236
	ds_bpermute_b32 v239, v192, v237
	s_waitcnt lgkmcnt(6)
; __device__ __forceinline__ float wave_sum(float v) {
; #pragma unroll
;     for (int o = 1; o < 64; o <<= 1) v += __shfl_xor(v, o);
;     return v;
; template <bool LN1>
; __device__ __forceinline__ void ln_phase(Frame& F, const bf16_t* Yin, const float* ga, const float* be, const float* modf, float* stats, bf16_t* ob16, float* of32) {
;     ...
;             for (int k = 0; k < 8; ++k) { pg8::unpack8(nx[k], v[k][0], v[k][1]);
;                 float s = ((v[k][0][0] + v[k][0][1]) + (v[k][0][2] + v[k][0][3])) + ((v[k][1][0] + v[k][1][1]) + (v[k][1][2] + v[k][1][3]));
;                 float q = ((v[k][0][0] * v[k][0][0] + v[k][0][1] * v[k][0][1]) + (v[k][0][2] * v[k][0][2] + v[k][0][3] * v[k][0][3])) + ((v[k][1][0] * v[k][1][0] + v[k][1][1] * v[k][1][1]) + (v[k][1][2] * v[k][1][2] + v[k][1][3] * v[k][1][3]));
;                 s = wave_sum(s); q = wave_sum(q);
;                 if (lane == 0) rd[k * 8 + w] = (f32x2){s, q}; }
	v_pk_add_f32 v[216:217], v[216:217], v[218:219]
	v_pk_add_f32 v[220:221], v[220:221], v[222:223]
	v_pk_add_f32 v[224:225], v[224:225], v[226:227]
	ds_bpermute_b32 v242, v192, v240
	ds_bpermute_b32 v243, v192, v241
	ds_bpermute_b32 v250, v192, v248
	ds_bpermute_b32 v251, v192, v249
	s_waitcnt lgkmcnt(4)
	v_pk_add_f32 v[228:229], v[228:229], v[230:231]
	v_pk_add_f32 v[232:233], v[232:233], v[234:235]
	v_pk_add_f32 v[236:237], v[236:237], v[238:239]
	ds_bpermute_b32 v218, v193, v216
	ds_bpermute_b32 v219, v193, v217
	ds_bpermute_b32 v222, v193, v220
	ds_bpermute_b32 v223, v193, v221
	ds_bpermute_b32 v226, v193, v224
	ds_bpermute_b32 v227, v193, v225
	s_waitcnt lgkmcnt(6)
	v_pk_add_f32 v[240:241], v[240:241], v[242:243]
	v_pk_add_f32 v[248:249], v[248:249], v[250:251]
	ds_bpermute_b32 v230, v193, v228
	ds_bpermute_b32 v231, v193, v229
	ds_bpermute_b32 v234, v193, v232
	ds_bpermute_b32 v235, v193, v233
	ds_bpermute_b32 v238, v193, v236
	ds_bpermute_b32 v239, v193, v237
	s_waitcnt lgkmcnt(6)
	v_pk_add_f32 v[216:217], v[216:217], v[218:219]
	v_pk_add_f32 v[220:221], v[220:221], v[222:223]
	v_pk_add_f32 v[224:225], v[224:225], v[226:227]
	ds_bpermute_b32 v242, v193, v240
	ds_bpermute_b32 v243, v193, v241
	ds_bpermute_b32 v250, v193, v248
	ds_bpermute_b32 v251, v193, v249
	s_waitcnt lgkmcnt(4)
	v_pk_add_f32 v[228:229], v[228:229], v[230:231]
	v_pk_add_f32 v[232:233], v[232:233], v[234:235]
	v_pk_add_f32 v[236:237], v[236:237], v[238:239]
	ds_bpermute_b32 v218, v194, v216
	ds_bpermute_b32 v219, v194, v217
	ds_bpermute_b32 v222, v194, v220
	ds_bpermute_b32 v223, v194, v221
	ds_bpermute_b32 v226, v194, v224
	ds_bpermute_b32 v227, v194, v225
	s_waitcnt lgkmcnt(6)
	v_pk_add_f32 v[240:241], v[240:241], v[242:243]
	v_pk_add_f32 v[248:249], v[248:249], v[250:251]
	ds_bpermute_b32 v230, v194, v228
	ds_bpermute_b32 v231, v194, v229
	ds_bpermute_b32 v234, v194, v232
	ds_bpermute_b32 v235, v194, v233
	ds_bpermute_b32 v238, v194, v236
	ds_bpermute_b32 v239, v194, v237
	s_waitcnt lgkmcnt(6)
	v_pk_add_f32 v[216:217], v[216:217], v[218:219]
	v_pk_add_f32 v[220:221], v[220:221], v[222:223]
	v_pk_add_f32 v[224:225], v[224:225], v[226:227]
	ds_bpermute_b32 v242, v194, v240
	ds_bpermute_b32 v243, v194, v241
	ds_bpermute_b32 v250, v194, v248
	ds_bpermute_b32 v251, v194, v249
	s_waitcnt lgkmcnt(4)
	v_pk_add_f32 v[228:229], v[228:229], v[230:231]
	v_pk_add_f32 v[232:233], v[232:233], v[234:235]
	v_pk_add_f32 v[236:237], v[236:237], v[238:239]
	ds_bpermute_b32 v218, v195, v216
	ds_bpermute_b32 v219, v195, v217
	ds_bpermute_b32 v222, v195, v220
	ds_bpermute_b32 v223, v195, v221
	ds_bpermute_b32 v226, v195, v224
	ds_bpermute_b32 v227, v195, v225
	s_waitcnt lgkmcnt(6)
	v_pk_add_f32 v[240:241], v[240:241], v[242:243]
	v_pk_add_f32 v[248:249], v[248:249], v[250:251]
	ds_bpermute_b32 v230, v195, v228
	ds_bpermute_b32 v231, v195, v229
	ds_bpermute_b32 v234, v195, v232
	ds_bpermute_b32 v235, v195, v233
	ds_bpermute_b32 v238, v195, v236
	ds_bpermute_b32 v239, v195, v237
	s_waitcnt lgkmcnt(6)
	v_pk_add_f32 v[216:217], v[216:217], v[218:219]
	v_pk_add_f32 v[220:221], v[220:221], v[222:223]
	v_pk_add_f32 v[224:225], v[224:225], v[226:227]
	ds_bpermute_b32 v242, v195, v240
	ds_bpermute_b32 v243, v195, v241
	ds_bpermute_b32 v250, v195, v248
	ds_bpermute_b32 v251, v195, v249
	s_waitcnt lgkmcnt(4)
	v_pk_add_f32 v[228:229], v[228:229], v[230:231]
	v_pk_add_f32 v[232:233], v[232:233], v[234:235]
	v_pk_add_f32 v[236:237], v[236:237], v[238:239]
	s_waitcnt lgkmcnt(0)
	v_pk_add_f32 v[240:241], v[240:241], v[242:243]
	v_pk_add_f32 v[248:249], v[248:249], v[250:251]
	s_and_saveexec_b64 s[2:3], s[0:1]
	s_cbranch_execz .LBB0_1344
	v_mov_b32_e32 v252, s16
	ds_write_b64 v252, v[216:217]
	ds_write_b64 v252, v[220:221] offset:64
	ds_write_b64 v252, v[224:225] offset:128
	ds_write_b64 v252, v[228:229] offset:192
	ds_write_b64 v252, v[232:233] offset:256
	ds_write_b64 v252, v[236:237] offset:320
	ds_write_b64 v252, v[240:241] offset:384
	ds_write_b64 v252, v[248:249] offset:448
	s_branch .LBB0_1344

; __global__ void __launch_bounds__(512, 2) fwd(Args args) {
	.amdhsa_kernel _Z3fwd4Args
		.amdhsa_group_segment_fixed_size 0
		.amdhsa_private_segment_fixed_size 0
		.amdhsa_kernarg_size 464
		.amdhsa_user_sgpr_count 2
		.amdhsa_user_sgpr_dispatch_ptr 0
		.amdhsa_user_sgpr_queue_ptr 0
		.amdhsa_user_sgpr_kernarg_segment_ptr 1
		.amdhsa_user_sgpr_dispatch_id 0
		.amdhsa_user_sgpr_kernarg_preload_length 0
		.amdhsa_user_sgpr_kernarg_preload_offset 0
		.amdhsa_user_sgpr_private_segment_size 0
		.amdhsa_uses_dynamic_stack 0
		.amdhsa_enable_private_segment 0
		.amdhsa_system_sgpr_workgroup_id_x 1
		.amdhsa_system_sgpr_workgroup_id_y 0
		.amdhsa_system_sgpr_workgroup_id_z 0
		.amdhsa_system_sgpr_workgroup_info 0
		.amdhsa_system_vgpr_workitem_id 0
		.amdhsa_next_free_vgpr 256
		.amdhsa_next_free_sgpr 98
		.amdhsa_accum_offset 256
		.amdhsa_reserve_vcc 1
		.amdhsa_float_round_mode_32 0
		.amdhsa_float_round_mode_16_64 0
		.amdhsa_float_denorm_mode_32 3
		.amdhsa_float_denorm_mode_16_64 3
		.amdhsa_dx10_clamp 1
		.amdhsa_ieee_mode 1
		.amdhsa_fp16_overflow 0
		.amdhsa_tg_split 0
		.amdhsa_exception_fp_ieee_invalid_op 0
		.amdhsa_exception_fp_denorm_src 0
		.amdhsa_exception_fp_ieee_div_zero 0
		.amdhsa_exception_fp_ieee_overflow 0
		.amdhsa_exception_fp_ieee_underflow 0
		.amdhsa_exception_fp_ieee_inexact 0
		.amdhsa_exception_int_div_zero 0
	.end_amdhsa_kernel

; __global__ void __launch_bounds__(512, 2) fwd(Args args) {
amdhsa.kernels:
  - .agpr_count:     0
    .args:
      - .offset:         0
        .size:           208
        .value_kind:     by_value
      - .offset:         208
        .size:           4
        .value_kind:     hidden_block_count_x
      - .offset:         212
        .size:           4
        .value_kind:     hidden_block_count_y
      - .offset:         216
        .size:           4
        .value_kind:     hidden_block_count_z
      - .offset:         220
        .size:           2
        .value_kind:     hidden_group_size_x
      - .offset:         222
        .size:           2
        .value_kind:     hidden_group_size_y
      - .offset:         224
        .size:           2
        .value_kind:     hidden_group_size_z
      - .offset:         226
        .size:           2
        .value_kind:     hidden_remainder_x
      - .offset:         228
        .size:           2
        .value_kind:     hidden_remainder_y
      - .offset:         230
        .size:           2
        .value_kind:     hidden_remainder_z
      - .offset:         248
        .size:           8
        .value_kind:     hidden_global_offset_x
      - .offset:         256
        .size:           8
        .value_kind:     hidden_global_offset_y
      - .offset:         264
        .size:           8
        .value_kind:     hidden_global_offset_z
      - .offset:         272
        .size:           2
        .value_kind:     hidden_grid_dims
      - .offset:         328
        .size:           4
        .value_kind:     hidden_dynamic_lds_size
    .group_segment_fixed_size: 0
    .kernarg_segment_align: 8
    .kernarg_segment_size: 464
    .language:       OpenCL C
    .language_version:
      - 2
      - 0
    .max_flat_workgroup_size: 512
    .name:           _Z3fwd4Args
    .private_segment_fixed_size: 0
    .sgpr_count:     104
    .sgpr_spill_count: 106
    .symbol:         _Z3fwd4Args.kd
    .uniform_work_group_size: 1
    .uses_dynamic_stack: false
    .vgpr_count:     256
    .vgpr_spill_count: 0
    .wavefront_size: 64
